# w_cq rows: both kernarg pointer reads issued together and the drain between the gain loads and the row loads removed
# speedup vs baseline: 1.0011x; 1.0011x over previous
.LBB0_216:
	s_waitcnt vmcnt(0)
	v_mov_b64_e32 v[6:7], s[92:93]
	flat_load_dwordx2 v[2:3], v[6:7] offset:64 sc0 sc1
	flat_load_dwordx2 v[130:131], v[6:7] offset:80 sc0 sc1
	s_waitcnt vmcnt(0)
	s_lshl_b32 s0, s25, 4
	s_lshl_b32 s1, s24, 1
	s_add_i32 s0, s0, s1
	s_ashr_i32 s1, s0, 31
	s_lshl_b64 s[4:5], s[0:1], 2
	s_lshl_b64 s[6:7], s[0:1], 14
	v_lshlrev_b64 v[8:9], 4, v[134:135]
	v_lshl_add_u64 v[12:13], v[134:135], 3, s[14:15]
	s_lshl_b32 s10, s24, 12
	s_and_b32 s10, s10, 0x1000
	s_waitcnt lgkmcnt(0)
	v_lshl_add_u64 v[2:3], v[2:3], 0, s[4:5]
	flat_load_dword v18, v[2:3]
	global_load_dword v128, v[2:3], off offset:4
	s_nop 0
	v_lshl_add_u64 v[2:3], v[130:131], 0, s[6:7]
	v_lshl_add_u64 v[10:11], v[2:3], 0, v[8:9]
	v_add_co_u32_e32 v212, vcc, 0x1000, v10
	s_nop 1
	v_addc_co_u32_e32 v213, vcc, 0, v11, vcc
	v_add_co_u32_e32 v228, vcc, 0x2000, v10
	s_nop 1
	v_addc_co_u32_e32 v229, vcc, 0, v11, vcc
	v_add_co_u32_e32 v244, vcc, 0x3000, v10
	s_nop 1
	v_addc_co_u32_e32 v245, vcc, 0, v11, vcc
	global_load_dwordx4 v[184:187], v[10:11], off nt
	global_load_dwordx4 v[188:191], v[10:11], off offset:1024 nt
	global_load_dwordx4 v[192:195], v[10:11], off offset:2048 nt
	global_load_dwordx4 v[196:199], v[10:11], off offset:3072 nt
	global_load_dwordx4 v[200:203], v[212:213], off nt
	global_load_dwordx4 v[204:207], v[212:213], off offset:1024 nt
	global_load_dwordx4 v[208:211], v[212:213], off offset:2048 nt
	global_load_dwordx4 v[212:215], v[212:213], off offset:3072 nt
	global_load_dwordx4 v[216:219], v[228:229], off nt
	global_load_dwordx4 v[220:223], v[228:229], off offset:1024 nt
	global_load_dwordx4 v[224:227], v[228:229], off offset:2048 nt
	global_load_dwordx4 v[228:231], v[228:229], off offset:3072 nt
	global_load_dwordx4 v[232:235], v[244:245], off nt
	global_load_dwordx4 v[236:239], v[244:245], off offset:1024 nt
	global_load_dwordx4 v[240:243], v[244:245], off offset:2048 nt
	global_load_dwordx4 v[244:247], v[244:245], off offset:3072 nt
	v_add_co_u32_e32 v76, vcc, 0x4000, v10
	s_nop 1
	v_addc_co_u32_e32 v77, vcc, 0, v11, vcc
	v_add_co_u32_e32 v92, vcc, 0x5000, v10
	s_nop 1
	v_addc_co_u32_e32 v93, vcc, 0, v11, vcc
	v_add_co_u32_e32 v108, vcc, 0x6000, v10
	s_nop 1
	v_addc_co_u32_e32 v109, vcc, 0, v11, vcc
	v_add_co_u32_e32 v124, vcc, 0x7000, v10
	s_nop 1
	v_addc_co_u32_e32 v125, vcc, 0, v11, vcc
	global_load_dwordx4 v[64:67], v[76:77], off nt
	global_load_dwordx4 v[68:71], v[76:77], off offset:1024 nt
	global_load_dwordx4 v[72:75], v[76:77], off offset:2048 nt
	global_load_dwordx4 v[76:79], v[76:77], off offset:3072 nt
	global_load_dwordx4 v[80:83], v[92:93], off nt
	global_load_dwordx4 v[84:87], v[92:93], off offset:1024 nt
	global_load_dwordx4 v[88:91], v[92:93], off offset:2048 nt
	global_load_dwordx4 v[92:95], v[92:93], off offset:3072 nt
	global_load_dwordx4 v[96:99], v[108:109], off nt
	global_load_dwordx4 v[100:103], v[108:109], off offset:1024 nt
	global_load_dwordx4 v[104:107], v[108:109], off offset:2048 nt
	global_load_dwordx4 v[108:111], v[108:109], off offset:3072 nt
	global_load_dwordx4 v[112:115], v[124:125], off nt
	global_load_dwordx4 v[116:119], v[124:125], off offset:1024 nt
	global_load_dwordx4 v[120:123], v[124:125], off offset:2048 nt
	global_load_dwordx4 v[124:127], v[124:125], off offset:3072 nt
	s_lshl_b64 s[6:7], s[0:1], 13
	v_lshl_add_u64 v[14:15], v[12:13], 0, s[6:7]
	s_movk_i32 s1, 0x1000
	v_add_co_u32_e32 v16, vcc, s1, v10
	s_movk_i32 s6, 0x2000
	s_nop 0
	v_addc_co_u32_e32 v17, vcc, 0, v11, vcc
	s_movk_i32 s7, 0x3000
	s_waitcnt vmcnt(0) lgkmcnt(0)
	v_mov_b32_e32 v2, v184
	v_mov_b32_e32 v3, v185
	v_mov_b32_e32 v4, v186
	v_mov_b32_e32 v5, v187
	v_mul_f32_e32 v2, v18, v2
	v_mul_f32_e32 v3, v18, v3
	v_mul_f32_e32 v4, v18, v4
	v_mul_f32_e32 v5, v18, v5
	v_cvt_pk_bf16_f32 v2, v2, v3
	v_cvt_pk_bf16_f32 v3, v4, v5
	global_store_dwordx2 v[14:15], v[2:3], off
	s_nop 1
	v_mov_b32_e32 v2, v188
	v_mov_b32_e32 v3, v189
	v_mov_b32_e32 v4, v190
	v_mov_b32_e32 v5, v191
	v_mul_f32_e32 v2, v18, v2
	v_mul_f32_e32 v3, v18, v3
	v_mul_f32_e32 v4, v18, v4
	v_mul_f32_e32 v5, v18, v5
	v_cvt_pk_bf16_f32 v2, v2, v3
	v_cvt_pk_bf16_f32 v3, v4, v5
	global_store_dwordx2 v[14:15], v[2:3], off offset:512
	s_nop 1
	v_mov_b32_e32 v2, v192
	v_mov_b32_e32 v3, v193
	v_mov_b32_e32 v4, v194
	v_mov_b32_e32 v5, v195
	v_mul_f32_e32 v2, v18, v2
	v_mul_f32_e32 v3, v18, v3
	v_mul_f32_e32 v4, v18, v4
	v_mul_f32_e32 v5, v18, v5
	v_cvt_pk_bf16_f32 v2, v2, v3
	v_cvt_pk_bf16_f32 v3, v4, v5
	global_store_dwordx2 v[14:15], v[2:3], off offset:1024
	s_nop 1
	v_mov_b32_e32 v2, v196
	v_mov_b32_e32 v3, v197
	v_mov_b32_e32 v4, v198
	v_mov_b32_e32 v5, v199
	v_mul_f32_e32 v2, v18, v2
	v_mul_f32_e32 v3, v18, v3
	v_mul_f32_e32 v4, v18, v4
	v_mul_f32_e32 v5, v18, v5
	v_cvt_pk_bf16_f32 v2, v2, v3
	v_cvt_pk_bf16_f32 v3, v4, v5
	global_store_dwordx2 v[14:15], v[2:3], off offset:1536
	s_nop 1
	v_mov_b32_e32 v2, v200
	v_mov_b32_e32 v3, v201
	v_mov_b32_e32 v4, v202
	v_mov_b32_e32 v5, v203
	v_mul_f32_e32 v2, v18, v2
	v_mul_f32_e32 v3, v18, v3
	v_mul_f32_e32 v4, v18, v4
	v_mul_f32_e32 v5, v18, v5
	v_cvt_pk_bf16_f32 v2, v2, v3
	v_cvt_pk_bf16_f32 v3, v4, v5
	global_store_dwordx2 v[14:15], v[2:3], off offset:2048
	s_nop 1
	v_mov_b32_e32 v2, v204
	v_mov_b32_e32 v3, v205
	v_mov_b32_e32 v4, v206
	v_mov_b32_e32 v5, v207
	v_mul_f32_e32 v2, v18, v2
	v_mul_f32_e32 v3, v18, v3
	v_mul_f32_e32 v4, v18, v4
	v_mul_f32_e32 v5, v18, v5
	v_cvt_pk_bf16_f32 v2, v2, v3
	v_cvt_pk_bf16_f32 v3, v4, v5
	global_store_dwordx2 v[14:15], v[2:3], off offset:2560
	s_nop 1
	v_mov_b32_e32 v2, v208
	v_mov_b32_e32 v3, v209
	v_mov_b32_e32 v4, v210
	v_mov_b32_e32 v5, v211
	v_mul_f32_e32 v2, v18, v2
	v_mul_f32_e32 v3, v18, v3
	v_mul_f32_e32 v4, v18, v4
	v_mul_f32_e32 v5, v18, v5
	v_cvt_pk_bf16_f32 v2, v2, v3
	v_cvt_pk_bf16_f32 v3, v4, v5
	global_store_dwordx2 v[14:15], v[2:3], off offset:3072
	s_nop 1
	v_mov_b32_e32 v2, v212
	v_mov_b32_e32 v3, v213
	v_mov_b32_e32 v4, v214
	v_mov_b32_e32 v5, v215
	v_add_co_u32_e32 v16, vcc, s6, v10
	v_mul_f32_e32 v2, v18, v2
	v_mul_f32_e32 v3, v18, v3
	v_addc_co_u32_e32 v17, vcc, 0, v11, vcc
	v_mul_f32_e32 v4, v18, v4
	v_mul_f32_e32 v5, v18, v5
	v_cvt_pk_bf16_f32 v2, v2, v3
	v_cvt_pk_bf16_f32 v3, v4, v5
	global_store_dwordx2 v[14:15], v[2:3], off offset:3584
	s_nop 1
	v_mov_b32_e32 v2, v216
	v_mov_b32_e32 v3, v217
	v_mov_b32_e32 v4, v218
	v_mov_b32_e32 v5, v219
	v_add_co_u32_e32 v14, vcc, s1, v14
	v_mul_f32_e32 v2, v18, v2
	s_nop 0
	v_addc_co_u32_e32 v15, vcc, 0, v15, vcc
	v_mul_f32_e32 v3, v18, v3
	v_mul_f32_e32 v4, v18, v4
	v_mul_f32_e32 v5, v18, v5
	v_cvt_pk_bf16_f32 v2, v2, v3
	v_cvt_pk_bf16_f32 v3, v4, v5
	global_store_dwordx2 v[14:15], v[2:3], off
	s_nop 1
	v_mov_b32_e32 v2, v220
	v_mov_b32_e32 v3, v221
	v_mov_b32_e32 v4, v222
	v_mov_b32_e32 v5, v223
	v_add_co_u32_e32 v10, vcc, s7, v10
	v_mul_f32_e32 v2, v18, v2
	v_mul_f32_e32 v3, v18, v3
	v_mul_f32_e32 v4, v18, v4
	v_mul_f32_e32 v5, v18, v5
	v_cvt_pk_bf16_f32 v2, v2, v3
	v_cvt_pk_bf16_f32 v3, v4, v5
	global_store_dwordx2 v[14:15], v[2:3], off offset:512
	s_nop 1
	v_mov_b32_e32 v2, v224
	v_mov_b32_e32 v3, v225
	v_mov_b32_e32 v4, v226
	v_mov_b32_e32 v5, v227
	v_addc_co_u32_e32 v11, vcc, 0, v11, vcc
	v_mul_f32_e32 v2, v18, v2
	v_mul_f32_e32 v3, v18, v3
	v_mul_f32_e32 v4, v18, v4
	v_mul_f32_e32 v5, v18, v5
	v_cvt_pk_bf16_f32 v2, v2, v3
	v_cvt_pk_bf16_f32 v3, v4, v5
	global_store_dwordx2 v[14:15], v[2:3], off offset:1024
	s_nop 1
	v_mov_b32_e32 v2, v228
	v_mov_b32_e32 v3, v229
	v_mov_b32_e32 v4, v230
	v_mov_b32_e32 v5, v231
	v_mul_f32_e32 v2, v18, v2
	v_mul_f32_e32 v3, v18, v3
	v_mul_f32_e32 v4, v18, v4
	v_mul_f32_e32 v5, v18, v5
	v_cvt_pk_bf16_f32 v2, v2, v3
	v_cvt_pk_bf16_f32 v3, v4, v5
	global_store_dwordx2 v[14:15], v[2:3], off offset:1536
	s_nop 1
	v_mov_b32_e32 v2, v232
	v_mov_b32_e32 v3, v233
	v_mov_b32_e32 v4, v234
	v_mov_b32_e32 v5, v235
	v_mul_f32_e32 v2, v18, v2
	v_mul_f32_e32 v3, v18, v3
	v_mul_f32_e32 v4, v18, v4
	v_mul_f32_e32 v5, v18, v5
	v_cvt_pk_bf16_f32 v2, v2, v3
	v_cvt_pk_bf16_f32 v3, v4, v5
	global_store_dwordx2 v[14:15], v[2:3], off offset:2048
	s_nop 1
	v_mov_b32_e32 v2, v236
	v_mov_b32_e32 v3, v237
	v_mov_b32_e32 v4, v238
	v_mov_b32_e32 v5, v239
	v_mul_f32_e32 v2, v18, v2
	v_mul_f32_e32 v3, v18, v3
	v_mul_f32_e32 v4, v18, v4
	v_mul_f32_e32 v5, v18, v5
	v_cvt_pk_bf16_f32 v2, v2, v3
	v_cvt_pk_bf16_f32 v3, v4, v5
	global_store_dwordx2 v[14:15], v[2:3], off offset:2560
	s_nop 1
	v_mov_b32_e32 v2, v240
	v_mov_b32_e32 v3, v241
	v_mov_b32_e32 v4, v242
	v_mov_b32_e32 v5, v243
	v_mul_f32_e32 v2, v18, v2
	v_mul_f32_e32 v3, v18, v3
	v_mul_f32_e32 v4, v18, v4
	v_mul_f32_e32 v5, v18, v5
	v_cvt_pk_bf16_f32 v2, v2, v3
	v_cvt_pk_bf16_f32 v3, v4, v5
	global_store_dwordx2 v[14:15], v[2:3], off offset:3072
	s_nop 1
	v_mov_b32_e32 v2, v244
	v_mov_b32_e32 v3, v245
	v_mov_b32_e32 v4, v246
	v_mov_b32_e32 v5, v247
	v_mul_f32_e32 v2, v18, v2
	v_mul_f32_e32 v3, v18, v3
	v_mul_f32_e32 v4, v18, v4
	v_mul_f32_e32 v5, v18, v5
	v_cvt_pk_bf16_f32 v2, v2, v3
	v_cvt_pk_bf16_f32 v3, v4, v5
	global_store_dwordx2 v[14:15], v[2:3], off offset:3584
	v_lshl_add_u64 v[2:3], v[2:3], 0, s[4:5]
	s_nop 0
	s_or_b32 s4, s0, 1
	s_ashr_i32 s5, s4, 31
	s_lshl_b64 s[8:9], s[4:5], 14
	s_lshl_b64 s[4:5], s[4:5], 13
	s_waitcnt lgkmcnt(0)
	v_lshl_add_u64 v[2:3], v[2:3], 0, s[8:9]
	v_lshl_add_u64 v[6:7], v[2:3], 0, v[8:9]
	v_lshl_add_u64 v[8:9], v[12:13], 0, s[4:5]
	v_add_co_u32_e32 v10, vcc, s1, v6
	s_add_i32 s4, s24, s57
	s_nop 0
	v_addc_co_u32_e32 v11, vcc, 0, v7, vcc
	s_lshl_b32 s4, s4, 3
	s_mov_b64 s[8:9], 0x26000100
	s_movk_i32 s5, 0xffe0
	s_waitcnt vmcnt(16) lgkmcnt(0)
	v_mov_b32_e32 v20, v128
	v_mov_b32_e32 v2, v64
	v_mov_b32_e32 v3, v65
	v_mov_b32_e32 v4, v66
	v_mov_b32_e32 v5, v67
	v_mul_f32_e32 v2, v20, v2
	v_mul_f32_e32 v3, v20, v3
	v_mul_f32_e32 v4, v20, v4
	v_mul_f32_e32 v5, v20, v5
	v_cvt_pk_bf16_f32 v2, v2, v3
	v_cvt_pk_bf16_f32 v3, v4, v5
	global_store_dwordx2 v[8:9], v[2:3], off
	s_nop 1
	v_mov_b32_e32 v2, v68
	v_mov_b32_e32 v3, v69
	v_mov_b32_e32 v4, v70
	v_mov_b32_e32 v5, v71
	v_mul_f32_e32 v2, v20, v2
	v_mul_f32_e32 v3, v20, v3
	v_mul_f32_e32 v4, v20, v4
	v_mul_f32_e32 v5, v20, v5
	v_cvt_pk_bf16_f32 v2, v2, v3
	v_cvt_pk_bf16_f32 v3, v4, v5
	global_store_dwordx2 v[8:9], v[2:3], off offset:512
	s_nop 1
	v_mov_b32_e32 v2, v72
	v_mov_b32_e32 v3, v73
	v_mov_b32_e32 v4, v74
	v_mov_b32_e32 v5, v75
	v_mul_f32_e32 v2, v20, v2
	v_mul_f32_e32 v3, v20, v3
	v_mul_f32_e32 v4, v20, v4
	v_mul_f32_e32 v5, v20, v5
	v_cvt_pk_bf16_f32 v2, v2, v3
	v_cvt_pk_bf16_f32 v3, v4, v5
	global_store_dwordx2 v[8:9], v[2:3], off offset:1024
	s_nop 1
	v_mov_b32_e32 v2, v76
	v_mov_b32_e32 v3, v77
	v_mov_b32_e32 v4, v78
	v_mov_b32_e32 v5, v79
	v_mul_f32_e32 v2, v20, v2
	v_mul_f32_e32 v3, v20, v3
	v_mul_f32_e32 v4, v20, v4
	v_mul_f32_e32 v5, v20, v5
	v_cvt_pk_bf16_f32 v2, v2, v3
	v_cvt_pk_bf16_f32 v3, v4, v5
	global_store_dwordx2 v[8:9], v[2:3], off offset:1536
	s_nop 1
	v_mov_b32_e32 v2, v80
	v_mov_b32_e32 v3, v81
	v_mov_b32_e32 v4, v82
	v_mov_b32_e32 v5, v83
	v_mul_f32_e32 v2, v20, v2
	v_mul_f32_e32 v3, v20, v3
	v_mul_f32_e32 v4, v20, v4
	v_mul_f32_e32 v5, v20, v5
	v_cvt_pk_bf16_f32 v2, v2, v3
	v_cvt_pk_bf16_f32 v3, v4, v5
	global_store_dwordx2 v[8:9], v[2:3], off offset:2048
	s_nop 1
	v_mov_b32_e32 v2, v84
	v_mov_b32_e32 v3, v85
	v_mov_b32_e32 v4, v86
	v_mov_b32_e32 v5, v87
	v_mul_f32_e32 v2, v20, v2
	v_mul_f32_e32 v3, v20, v3
	v_mul_f32_e32 v4, v20, v4
	v_mul_f32_e32 v5, v20, v5
	v_cvt_pk_bf16_f32 v2, v2, v3
	v_cvt_pk_bf16_f32 v3, v4, v5
	global_store_dwordx2 v[8:9], v[2:3], off offset:2560
	s_nop 1
	v_mov_b32_e32 v2, v88
	v_mov_b32_e32 v3, v89
	v_mov_b32_e32 v4, v90
	v_mov_b32_e32 v5, v91
	v_mul_f32_e32 v2, v20, v2
	v_mul_f32_e32 v3, v20, v3
	v_mul_f32_e32 v4, v20, v4
	v_mul_f32_e32 v5, v20, v5
	v_cvt_pk_bf16_f32 v2, v2, v3
	v_cvt_pk_bf16_f32 v3, v4, v5
	global_store_dwordx2 v[8:9], v[2:3], off offset:3072
	s_nop 1
	v_mov_b32_e32 v2, v92
	v_mov_b32_e32 v3, v93
	v_mov_b32_e32 v4, v94
	v_mov_b32_e32 v5, v95
	v_add_co_u32_e32 v10, vcc, s6, v6
	v_mul_f32_e32 v2, v20, v2
	v_mul_f32_e32 v3, v20, v3
	v_addc_co_u32_e32 v11, vcc, 0, v7, vcc
	v_mul_f32_e32 v4, v20, v4
	v_mul_f32_e32 v5, v20, v5
	v_cvt_pk_bf16_f32 v2, v2, v3
	v_cvt_pk_bf16_f32 v3, v4, v5
	global_store_dwordx2 v[8:9], v[2:3], off offset:3584
	s_nop 1
	v_mov_b32_e32 v2, v96
	v_mov_b32_e32 v3, v97
	v_mov_b32_e32 v4, v98
	v_mov_b32_e32 v5, v99
	v_add_co_u32_e32 v16, vcc, s1, v8
	v_lshlrev_b32_e32 v8, 3, v150
	s_nop 0
	v_addc_co_u32_e32 v17, vcc, 0, v9, vcc
	v_add_co_u32_e32 v6, vcc, s7, v6
	v_ashrrev_i32_e32 v9, 31, v8
	s_nop 0
	v_addc_co_u32_e32 v7, vcc, 0, v7, vcc
	v_lshlrev_b64 v[18:19], 1, v[8:9]
	s_mov_b64 s[6:7], 0x4e500100
	s_mov_b64 s[0:1], 0x200
	v_mul_f32_e32 v2, v20, v2
	v_mul_f32_e32 v3, v20, v3
	v_mul_f32_e32 v4, v20, v4
	v_mul_f32_e32 v5, v20, v5
	v_cvt_pk_bf16_f32 v2, v2, v3
	v_cvt_pk_bf16_f32 v3, v4, v5
	global_store_dwordx2 v[16:17], v[2:3], off
	s_nop 1
	v_mov_b32_e32 v2, v100
	v_mov_b32_e32 v3, v101
	v_mov_b32_e32 v4, v102
	v_mov_b32_e32 v5, v103
	v_mul_f32_e32 v2, v20, v2
	v_mul_f32_e32 v3, v20, v3
	v_mul_f32_e32 v4, v20, v4
	v_mul_f32_e32 v5, v20, v5
	v_cvt_pk_bf16_f32 v2, v2, v3
	v_cvt_pk_bf16_f32 v3, v4, v5
	global_store_dwordx2 v[16:17], v[2:3], off offset:512
	s_nop 1
	v_mov_b32_e32 v2, v104
	v_mov_b32_e32 v3, v105
	v_mov_b32_e32 v4, v106
	v_mov_b32_e32 v5, v107
	v_mul_f32_e32 v2, v20, v2
	v_mul_f32_e32 v3, v20, v3
	v_mul_f32_e32 v4, v20, v4
	v_mul_f32_e32 v5, v20, v5
	v_cvt_pk_bf16_f32 v2, v2, v3
	v_cvt_pk_bf16_f32 v3, v4, v5
	global_store_dwordx2 v[16:17], v[2:3], off offset:1024
	s_nop 1
	v_mov_b32_e32 v2, v108
	v_mov_b32_e32 v3, v109
	v_mov_b32_e32 v4, v110
	v_mov_b32_e32 v5, v111
	v_bfi_b32 v10, -16, s4, v134
	v_ashrrev_i32_e32 v11, 31, v10
	v_lshlrev_b64 v[10:11], 13, v[10:11]
	v_or_b32_e32 v10, s10, v10
	v_lshl_add_u64 v[10:11], v[10:11], 0, v[18:19]
	v_lshl_add_u64 v[10:11], s[78:79], 0, v[10:11]
	v_lshl_add_u64 v[10:11], v[10:11], 0, s[8:9]
	v_mul_f32_e32 v2, v20, v2
	v_mul_f32_e32 v3, v20, v3
	v_mul_f32_e32 v4, v20, v4
	v_mul_f32_e32 v5, v20, v5
	v_cvt_pk_bf16_f32 v2, v2, v3
	v_cvt_pk_bf16_f32 v3, v4, v5
	global_store_dwordx2 v[16:17], v[2:3], off offset:1536
	s_nop 1
	v_mov_b32_e32 v2, v112
	v_mov_b32_e32 v3, v113
	v_mov_b32_e32 v4, v114
	v_mov_b32_e32 v5, v115
	v_mul_f32_e32 v2, v20, v2
	v_mul_f32_e32 v3, v20, v3
	v_mul_f32_e32 v4, v20, v4
	v_mul_f32_e32 v5, v20, v5
	v_cvt_pk_bf16_f32 v2, v2, v3
	v_cvt_pk_bf16_f32 v3, v4, v5
	global_store_dwordx2 v[16:17], v[2:3], off offset:2048
	s_nop 1
	v_mov_b32_e32 v2, v116
	v_mov_b32_e32 v3, v117
	v_mov_b32_e32 v4, v118
	v_mov_b32_e32 v5, v119
	v_mul_f32_e32 v2, v20, v2
	v_mul_f32_e32 v3, v20, v3
	v_mul_f32_e32 v4, v20, v4
	v_mul_f32_e32 v5, v20, v5
	v_cvt_pk_bf16_f32 v2, v2, v3
	v_cvt_pk_bf16_f32 v3, v4, v5
	global_store_dwordx2 v[16:17], v[2:3], off offset:2560
	s_nop 1
	v_mov_b32_e32 v2, v120
	v_mov_b32_e32 v3, v121
	v_mov_b32_e32 v4, v122
	v_mov_b32_e32 v5, v123
	v_mul_f32_e32 v2, v20, v2
	v_mul_f32_e32 v3, v20, v3
	v_mul_f32_e32 v4, v20, v4
	v_mul_f32_e32 v5, v20, v5
	v_cvt_pk_bf16_f32 v2, v2, v3
	v_cvt_pk_bf16_f32 v3, v4, v5
	global_store_dwordx2 v[16:17], v[2:3], off offset:3072
	s_nop 1
	v_mov_b32_e32 v12, v124
	v_mov_b32_e32 v13, v125
	v_mov_b32_e32 v14, v126
	v_mov_b32_e32 v15, v127
	v_and_b32_e32 v6, 15, v134
	v_mov_b32_e32 v3, 0
	v_lshl_or_b32 v2, v6, 13, s10
	v_lshl_add_u64 v[8:9], v[2:3], 0, v[18:19]
	v_lshl_add_u64 v[8:9], s[78:79], 0, v[8:9]
	v_mov_b32_e32 v4, v3
	v_mov_b32_e32 v2, v3
	v_lshl_add_u64 v[8:9], v[8:9], 0, s[6:7]
	v_mul_f32_e32 v5, v20, v12
	v_mul_f32_e32 v7, v20, v13
	v_mul_f32_e32 v13, v20, v14
	v_cvt_pk_bf16_f32 v12, v5, v7
	v_mov_b32_e32 v5, v3
	v_mul_f32_e32 v14, v20, v15
	v_cvt_pk_bf16_f32 v13, v13, v14
	global_store_dwordx2 v[16:17], v[12:13], off offset:3584

.LBB0_328:
	s_waitcnt vmcnt(0)
	v_mov_b64_e32 v[6:7], s[92:93]
	flat_load_dwordx2 v[2:3], v[6:7] offset:64 sc0 sc1
	flat_load_dwordx2 v[130:131], v[6:7] offset:80 sc0 sc1
	s_waitcnt vmcnt(0)
	s_lshl_b32 s0, s27, 4
	s_lshl_b32 s1, s26, 1
	s_add_i32 s0, s0, s1
	s_ashr_i32 s1, s0, 31
	s_lshl_b64 s[6:7], s[0:1], 2
	s_lshl_b64 s[8:9], s[0:1], 14
	v_lshlrev_b64 v[8:9], 4, v[134:135]
	v_lshl_add_u64 v[12:13], v[134:135], 3, s[14:15]
	s_lshl_b32 s12, s26, 12
	s_and_b32 s12, s12, 0x1000
	s_waitcnt lgkmcnt(0)
	v_lshl_add_u64 v[2:3], v[2:3], 0, s[6:7]
	flat_load_dword v18, v[2:3]
	global_load_dword v128, v[2:3], off offset:4
	s_nop 0
	v_lshl_add_u64 v[2:3], v[130:131], 0, s[8:9]
	v_lshl_add_u64 v[10:11], v[2:3], 0, v[8:9]
	v_add_co_u32_e32 v212, vcc, 0x1000, v10
	s_nop 1
	v_addc_co_u32_e32 v213, vcc, 0, v11, vcc
	v_add_co_u32_e32 v228, vcc, 0x2000, v10
	s_nop 1
	v_addc_co_u32_e32 v229, vcc, 0, v11, vcc
	v_add_co_u32_e32 v244, vcc, 0x3000, v10
	s_nop 1
	v_addc_co_u32_e32 v245, vcc, 0, v11, vcc
	global_load_dwordx4 v[184:187], v[10:11], off nt
	global_load_dwordx4 v[188:191], v[10:11], off offset:1024 nt
	global_load_dwordx4 v[192:195], v[10:11], off offset:2048 nt
	global_load_dwordx4 v[196:199], v[10:11], off offset:3072 nt
	global_load_dwordx4 v[200:203], v[212:213], off nt
	global_load_dwordx4 v[204:207], v[212:213], off offset:1024 nt
	global_load_dwordx4 v[208:211], v[212:213], off offset:2048 nt
	global_load_dwordx4 v[212:215], v[212:213], off offset:3072 nt
	global_load_dwordx4 v[216:219], v[228:229], off nt
	global_load_dwordx4 v[220:223], v[228:229], off offset:1024 nt
	global_load_dwordx4 v[224:227], v[228:229], off offset:2048 nt
	global_load_dwordx4 v[228:231], v[228:229], off offset:3072 nt
	global_load_dwordx4 v[232:235], v[244:245], off nt
	global_load_dwordx4 v[236:239], v[244:245], off offset:1024 nt
	global_load_dwordx4 v[240:243], v[244:245], off offset:2048 nt
	global_load_dwordx4 v[244:247], v[244:245], off offset:3072 nt
	v_add_co_u32_e32 v76, vcc, 0x4000, v10
	s_nop 1
	v_addc_co_u32_e32 v77, vcc, 0, v11, vcc
	v_add_co_u32_e32 v92, vcc, 0x5000, v10
	s_nop 1
	v_addc_co_u32_e32 v93, vcc, 0, v11, vcc
	v_add_co_u32_e32 v108, vcc, 0x6000, v10
	s_nop 1
	v_addc_co_u32_e32 v109, vcc, 0, v11, vcc
	v_add_co_u32_e32 v124, vcc, 0x7000, v10
	s_nop 1
	v_addc_co_u32_e32 v125, vcc, 0, v11, vcc
	global_load_dwordx4 v[64:67], v[76:77], off nt
	global_load_dwordx4 v[68:71], v[76:77], off offset:1024 nt
	global_load_dwordx4 v[72:75], v[76:77], off offset:2048 nt
	global_load_dwordx4 v[76:79], v[76:77], off offset:3072 nt
	global_load_dwordx4 v[80:83], v[92:93], off nt
	global_load_dwordx4 v[84:87], v[92:93], off offset:1024 nt
	global_load_dwordx4 v[88:91], v[92:93], off offset:2048 nt
	global_load_dwordx4 v[92:95], v[92:93], off offset:3072 nt
	global_load_dwordx4 v[96:99], v[108:109], off nt
	global_load_dwordx4 v[100:103], v[108:109], off offset:1024 nt
	global_load_dwordx4 v[104:107], v[108:109], off offset:2048 nt
	global_load_dwordx4 v[108:111], v[108:109], off offset:3072 nt
	global_load_dwordx4 v[112:115], v[124:125], off nt
	global_load_dwordx4 v[116:119], v[124:125], off offset:1024 nt
	global_load_dwordx4 v[120:123], v[124:125], off offset:2048 nt
	global_load_dwordx4 v[124:127], v[124:125], off offset:3072 nt
	s_lshl_b64 s[8:9], s[0:1], 13
	v_lshl_add_u64 v[14:15], v[12:13], 0, s[8:9]
	s_movk_i32 s1, 0x1000
	v_add_co_u32_e32 v16, vcc, s1, v10
	s_movk_i32 s8, 0x2000
	s_nop 0
	v_addc_co_u32_e32 v17, vcc, 0, v11, vcc
	s_movk_i32 s9, 0x3000
	s_waitcnt vmcnt(0) lgkmcnt(0)
	v_mov_b32_e32 v2, v184
	v_mov_b32_e32 v3, v185
	v_mov_b32_e32 v4, v186
	v_mov_b32_e32 v5, v187
	v_mul_f32_e32 v2, v18, v2
	v_mul_f32_e32 v3, v18, v3
	v_mul_f32_e32 v4, v18, v4
	v_mul_f32_e32 v5, v18, v5
	v_cvt_pk_bf16_f32 v2, v2, v3
	v_cvt_pk_bf16_f32 v3, v4, v5
	global_store_dwordx2 v[14:15], v[2:3], off
	s_nop 1
	v_mov_b32_e32 v2, v188
	v_mov_b32_e32 v3, v189
	v_mov_b32_e32 v4, v190
	v_mov_b32_e32 v5, v191
	v_mul_f32_e32 v2, v18, v2
	v_mul_f32_e32 v3, v18, v3
	v_mul_f32_e32 v4, v18, v4
	v_mul_f32_e32 v5, v18, v5
	v_cvt_pk_bf16_f32 v2, v2, v3
	v_cvt_pk_bf16_f32 v3, v4, v5
	global_store_dwordx2 v[14:15], v[2:3], off offset:512
	s_nop 1
	v_mov_b32_e32 v2, v192
	v_mov_b32_e32 v3, v193
	v_mov_b32_e32 v4, v194
	v_mov_b32_e32 v5, v195
	v_mul_f32_e32 v2, v18, v2
	v_mul_f32_e32 v3, v18, v3
	v_mul_f32_e32 v4, v18, v4
	v_mul_f32_e32 v5, v18, v5
	v_cvt_pk_bf16_f32 v2, v2, v3
	v_cvt_pk_bf16_f32 v3, v4, v5
	global_store_dwordx2 v[14:15], v[2:3], off offset:1024
	s_nop 1
	v_mov_b32_e32 v2, v196
	v_mov_b32_e32 v3, v197
	v_mov_b32_e32 v4, v198
	v_mov_b32_e32 v5, v199
	v_mul_f32_e32 v2, v18, v2
	v_mul_f32_e32 v3, v18, v3
	v_mul_f32_e32 v4, v18, v4
	v_mul_f32_e32 v5, v18, v5
	v_cvt_pk_bf16_f32 v2, v2, v3
	v_cvt_pk_bf16_f32 v3, v4, v5
	global_store_dwordx2 v[14:15], v[2:3], off offset:1536
	s_nop 1
	v_mov_b32_e32 v2, v200
	v_mov_b32_e32 v3, v201
	v_mov_b32_e32 v4, v202
	v_mov_b32_e32 v5, v203
	v_mul_f32_e32 v2, v18, v2
	v_mul_f32_e32 v3, v18, v3
	v_mul_f32_e32 v4, v18, v4
	v_mul_f32_e32 v5, v18, v5
	v_cvt_pk_bf16_f32 v2, v2, v3
	v_cvt_pk_bf16_f32 v3, v4, v5
	global_store_dwordx2 v[14:15], v[2:3], off offset:2048
	s_nop 1
	v_mov_b32_e32 v2, v204
	v_mov_b32_e32 v3, v205
	v_mov_b32_e32 v4, v206
	v_mov_b32_e32 v5, v207
	v_mul_f32_e32 v2, v18, v2
	v_mul_f32_e32 v3, v18, v3
	v_mul_f32_e32 v4, v18, v4
	v_mul_f32_e32 v5, v18, v5
	v_cvt_pk_bf16_f32 v2, v2, v3
	v_cvt_pk_bf16_f32 v3, v4, v5
	global_store_dwordx2 v[14:15], v[2:3], off offset:2560
	s_nop 1
	v_mov_b32_e32 v2, v208
	v_mov_b32_e32 v3, v209
	v_mov_b32_e32 v4, v210
	v_mov_b32_e32 v5, v211
	v_mul_f32_e32 v2, v18, v2
	v_mul_f32_e32 v3, v18, v3
	v_mul_f32_e32 v4, v18, v4
	v_mul_f32_e32 v5, v18, v5
	v_cvt_pk_bf16_f32 v2, v2, v3
	v_cvt_pk_bf16_f32 v3, v4, v5
	global_store_dwordx2 v[14:15], v[2:3], off offset:3072
	s_nop 1
	v_mov_b32_e32 v2, v212
	v_mov_b32_e32 v3, v213
	v_mov_b32_e32 v4, v214
	v_mov_b32_e32 v5, v215
	v_add_co_u32_e32 v16, vcc, s8, v10
	v_mul_f32_e32 v2, v18, v2
	v_mul_f32_e32 v3, v18, v3
	v_addc_co_u32_e32 v17, vcc, 0, v11, vcc
	v_mul_f32_e32 v4, v18, v4
	v_mul_f32_e32 v5, v18, v5
	v_cvt_pk_bf16_f32 v2, v2, v3
	v_cvt_pk_bf16_f32 v3, v4, v5
	global_store_dwordx2 v[14:15], v[2:3], off offset:3584
	s_nop 1
	v_mov_b32_e32 v2, v216
	v_mov_b32_e32 v3, v217
	v_mov_b32_e32 v4, v218
	v_mov_b32_e32 v5, v219
	v_add_co_u32_e32 v14, vcc, s1, v14
	v_mul_f32_e32 v2, v18, v2
	s_nop 0
	v_addc_co_u32_e32 v15, vcc, 0, v15, vcc
	v_mul_f32_e32 v3, v18, v3
	v_mul_f32_e32 v4, v18, v4
	v_mul_f32_e32 v5, v18, v5
	v_cvt_pk_bf16_f32 v2, v2, v3
	v_cvt_pk_bf16_f32 v3, v4, v5
	global_store_dwordx2 v[14:15], v[2:3], off
	s_nop 1
	v_mov_b32_e32 v2, v220
	v_mov_b32_e32 v3, v221
	v_mov_b32_e32 v4, v222
	v_mov_b32_e32 v5, v223
	v_add_co_u32_e32 v10, vcc, s9, v10
	v_mul_f32_e32 v2, v18, v2
	v_mul_f32_e32 v3, v18, v3
	v_mul_f32_e32 v4, v18, v4
	v_mul_f32_e32 v5, v18, v5
	v_cvt_pk_bf16_f32 v2, v2, v3
	v_cvt_pk_bf16_f32 v3, v4, v5
	global_store_dwordx2 v[14:15], v[2:3], off offset:512
	s_nop 1
	v_mov_b32_e32 v2, v224
	v_mov_b32_e32 v3, v225
	v_mov_b32_e32 v4, v226
	v_mov_b32_e32 v5, v227
	v_addc_co_u32_e32 v11, vcc, 0, v11, vcc
	v_mul_f32_e32 v2, v18, v2
	v_mul_f32_e32 v3, v18, v3
	v_mul_f32_e32 v4, v18, v4
	v_mul_f32_e32 v5, v18, v5
	v_cvt_pk_bf16_f32 v2, v2, v3
	v_cvt_pk_bf16_f32 v3, v4, v5
	global_store_dwordx2 v[14:15], v[2:3], off offset:1024
	s_nop 1
	v_mov_b32_e32 v2, v228
	v_mov_b32_e32 v3, v229
	v_mov_b32_e32 v4, v230
	v_mov_b32_e32 v5, v231
	v_mul_f32_e32 v2, v18, v2
	v_mul_f32_e32 v3, v18, v3
	v_mul_f32_e32 v4, v18, v4
	v_mul_f32_e32 v5, v18, v5
	v_cvt_pk_bf16_f32 v2, v2, v3
	v_cvt_pk_bf16_f32 v3, v4, v5
	global_store_dwordx2 v[14:15], v[2:3], off offset:1536
	s_nop 1
	v_mov_b32_e32 v2, v232
	v_mov_b32_e32 v3, v233
	v_mov_b32_e32 v4, v234
	v_mov_b32_e32 v5, v235
	v_mul_f32_e32 v2, v18, v2
	v_mul_f32_e32 v3, v18, v3
	v_mul_f32_e32 v4, v18, v4
	v_mul_f32_e32 v5, v18, v5
	v_cvt_pk_bf16_f32 v2, v2, v3
	v_cvt_pk_bf16_f32 v3, v4, v5
	global_store_dwordx2 v[14:15], v[2:3], off offset:2048
	s_nop 1
	v_mov_b32_e32 v2, v236
	v_mov_b32_e32 v3, v237
	v_mov_b32_e32 v4, v238
	v_mov_b32_e32 v5, v239
	v_mul_f32_e32 v2, v18, v2
	v_mul_f32_e32 v3, v18, v3
	v_mul_f32_e32 v4, v18, v4
	v_mul_f32_e32 v5, v18, v5
	v_cvt_pk_bf16_f32 v2, v2, v3
	v_cvt_pk_bf16_f32 v3, v4, v5
	global_store_dwordx2 v[14:15], v[2:3], off offset:2560
	s_nop 1
	v_mov_b32_e32 v2, v240
	v_mov_b32_e32 v3, v241
	v_mov_b32_e32 v4, v242
	v_mov_b32_e32 v5, v243
	v_mul_f32_e32 v2, v18, v2
	v_mul_f32_e32 v3, v18, v3
	v_mul_f32_e32 v4, v18, v4
	v_mul_f32_e32 v5, v18, v5
	v_cvt_pk_bf16_f32 v2, v2, v3
	v_cvt_pk_bf16_f32 v3, v4, v5
	global_store_dwordx2 v[14:15], v[2:3], off offset:3072
	s_nop 1
	v_mov_b32_e32 v2, v244
	v_mov_b32_e32 v3, v245
	v_mov_b32_e32 v4, v246
	v_mov_b32_e32 v5, v247
	v_mul_f32_e32 v2, v18, v2
	v_mul_f32_e32 v3, v18, v3
	v_mul_f32_e32 v4, v18, v4
	v_mul_f32_e32 v5, v18, v5
	v_cvt_pk_bf16_f32 v2, v2, v3
	v_cvt_pk_bf16_f32 v3, v4, v5
	global_store_dwordx2 v[14:15], v[2:3], off offset:3584
	v_lshl_add_u64 v[2:3], v[2:3], 0, s[6:7]
	s_nop 0
	s_or_b32 s6, s0, 1
	s_ashr_i32 s7, s6, 31
	s_lshl_b64 s[10:11], s[6:7], 14
	s_lshl_b64 s[6:7], s[6:7], 13
	s_waitcnt lgkmcnt(0)
	v_lshl_add_u64 v[2:3], v[2:3], 0, s[10:11]
	v_lshl_add_u64 v[6:7], v[2:3], 0, v[8:9]
	v_lshl_add_u64 v[8:9], v[12:13], 0, s[6:7]
	v_add_co_u32_e32 v10, vcc, s1, v6
	s_add_i32 s6, s26, s57
	s_nop 0
	v_addc_co_u32_e32 v11, vcc, 0, v7, vcc
	s_lshl_b32 s6, s6, 3
	s_mov_b64 s[10:11], 0x26000100
	s_movk_i32 s7, 0xffe0
	s_waitcnt vmcnt(16) lgkmcnt(0)
	v_mov_b32_e32 v20, v128
	v_mov_b32_e32 v2, v64
	v_mov_b32_e32 v3, v65
	v_mov_b32_e32 v4, v66
	v_mov_b32_e32 v5, v67
	v_mul_f32_e32 v2, v20, v2
	v_mul_f32_e32 v3, v20, v3
	v_mul_f32_e32 v4, v20, v4
	v_mul_f32_e32 v5, v20, v5
	v_cvt_pk_bf16_f32 v2, v2, v3
	v_cvt_pk_bf16_f32 v3, v4, v5
	global_store_dwordx2 v[8:9], v[2:3], off
	s_nop 1
	v_mov_b32_e32 v2, v68
	v_mov_b32_e32 v3, v69
	v_mov_b32_e32 v4, v70
	v_mov_b32_e32 v5, v71
	v_mul_f32_e32 v2, v20, v2
	v_mul_f32_e32 v3, v20, v3
	v_mul_f32_e32 v4, v20, v4
	v_mul_f32_e32 v5, v20, v5
	v_cvt_pk_bf16_f32 v2, v2, v3
	v_cvt_pk_bf16_f32 v3, v4, v5
	global_store_dwordx2 v[8:9], v[2:3], off offset:512
	s_nop 1
	v_mov_b32_e32 v2, v72
	v_mov_b32_e32 v3, v73
	v_mov_b32_e32 v4, v74
	v_mov_b32_e32 v5, v75
	v_mul_f32_e32 v2, v20, v2
	v_mul_f32_e32 v3, v20, v3
	v_mul_f32_e32 v4, v20, v4
	v_mul_f32_e32 v5, v20, v5
	v_cvt_pk_bf16_f32 v2, v2, v3
	v_cvt_pk_bf16_f32 v3, v4, v5
	global_store_dwordx2 v[8:9], v[2:3], off offset:1024
	s_nop 1
	v_mov_b32_e32 v2, v76
	v_mov_b32_e32 v3, v77
	v_mov_b32_e32 v4, v78
	v_mov_b32_e32 v5, v79
	v_mul_f32_e32 v2, v20, v2
	v_mul_f32_e32 v3, v20, v3
	v_mul_f32_e32 v4, v20, v4
	v_mul_f32_e32 v5, v20, v5
	v_cvt_pk_bf16_f32 v2, v2, v3
	v_cvt_pk_bf16_f32 v3, v4, v5
	global_store_dwordx2 v[8:9], v[2:3], off offset:1536
	s_nop 1
	v_mov_b32_e32 v2, v80
	v_mov_b32_e32 v3, v81
	v_mov_b32_e32 v4, v82
	v_mov_b32_e32 v5, v83
	v_mul_f32_e32 v2, v20, v2
	v_mul_f32_e32 v3, v20, v3
	v_mul_f32_e32 v4, v20, v4
	v_mul_f32_e32 v5, v20, v5
	v_cvt_pk_bf16_f32 v2, v2, v3
	v_cvt_pk_bf16_f32 v3, v4, v5
	global_store_dwordx2 v[8:9], v[2:3], off offset:2048
	s_nop 1
	v_mov_b32_e32 v2, v84
	v_mov_b32_e32 v3, v85
	v_mov_b32_e32 v4, v86
	v_mov_b32_e32 v5, v87
	v_mul_f32_e32 v2, v20, v2
	v_mul_f32_e32 v3, v20, v3
	v_mul_f32_e32 v4, v20, v4
	v_mul_f32_e32 v5, v20, v5
	v_cvt_pk_bf16_f32 v2, v2, v3
	v_cvt_pk_bf16_f32 v3, v4, v5
	global_store_dwordx2 v[8:9], v[2:3], off offset:2560
	s_nop 1
	v_mov_b32_e32 v2, v88
	v_mov_b32_e32 v3, v89
	v_mov_b32_e32 v4, v90
	v_mov_b32_e32 v5, v91
	v_mul_f32_e32 v2, v20, v2
	v_mul_f32_e32 v3, v20, v3
	v_mul_f32_e32 v4, v20, v4
	v_mul_f32_e32 v5, v20, v5
	v_cvt_pk_bf16_f32 v2, v2, v3
	v_cvt_pk_bf16_f32 v3, v4, v5
	global_store_dwordx2 v[8:9], v[2:3], off offset:3072
	s_nop 1
	v_mov_b32_e32 v2, v92
	v_mov_b32_e32 v3, v93
	v_mov_b32_e32 v4, v94
	v_mov_b32_e32 v5, v95
	v_add_co_u32_e32 v10, vcc, s8, v6
	v_mul_f32_e32 v2, v20, v2
	v_mul_f32_e32 v3, v20, v3
	v_addc_co_u32_e32 v11, vcc, 0, v7, vcc
	v_mul_f32_e32 v4, v20, v4
	v_mul_f32_e32 v5, v20, v5
	v_cvt_pk_bf16_f32 v2, v2, v3
	v_cvt_pk_bf16_f32 v3, v4, v5
	global_store_dwordx2 v[8:9], v[2:3], off offset:3584
	s_nop 1
	v_mov_b32_e32 v2, v96
	v_mov_b32_e32 v3, v97
	v_mov_b32_e32 v4, v98
	v_mov_b32_e32 v5, v99
	v_add_co_u32_e32 v16, vcc, s1, v8
	v_lshlrev_b32_e32 v8, 3, v150
	s_nop 0
	v_addc_co_u32_e32 v17, vcc, 0, v9, vcc
	v_add_co_u32_e32 v6, vcc, s9, v6
	v_ashrrev_i32_e32 v9, 31, v8
	s_nop 0
	v_addc_co_u32_e32 v7, vcc, 0, v7, vcc
	v_lshlrev_b64 v[18:19], 1, v[8:9]
	s_mov_b64 s[8:9], 0x4e500100
	s_mov_b64 s[0:1], 0x200
	v_mul_f32_e32 v2, v20, v2
	v_mul_f32_e32 v3, v20, v3
	v_mul_f32_e32 v4, v20, v4
	v_mul_f32_e32 v5, v20, v5
	v_cvt_pk_bf16_f32 v2, v2, v3
	v_cvt_pk_bf16_f32 v3, v4, v5
	global_store_dwordx2 v[16:17], v[2:3], off
	s_nop 1
	v_mov_b32_e32 v2, v100
	v_mov_b32_e32 v3, v101
	v_mov_b32_e32 v4, v102
	v_mov_b32_e32 v5, v103
	v_mul_f32_e32 v2, v20, v2
	v_mul_f32_e32 v3, v20, v3
	v_mul_f32_e32 v4, v20, v4
	v_mul_f32_e32 v5, v20, v5
	v_cvt_pk_bf16_f32 v2, v2, v3
	v_cvt_pk_bf16_f32 v3, v4, v5
	global_store_dwordx2 v[16:17], v[2:3], off offset:512
	s_nop 1
	v_mov_b32_e32 v2, v104
	v_mov_b32_e32 v3, v105
	v_mov_b32_e32 v4, v106
	v_mov_b32_e32 v5, v107
	v_mul_f32_e32 v2, v20, v2
	v_mul_f32_e32 v3, v20, v3
	v_mul_f32_e32 v4, v20, v4
	v_mul_f32_e32 v5, v20, v5
	v_cvt_pk_bf16_f32 v2, v2, v3
	v_cvt_pk_bf16_f32 v3, v4, v5
	global_store_dwordx2 v[16:17], v[2:3], off offset:1024
	s_nop 1
	v_mov_b32_e32 v2, v108
	v_mov_b32_e32 v3, v109
	v_mov_b32_e32 v4, v110
	v_mov_b32_e32 v5, v111
	v_bfi_b32 v10, -16, s6, v134
	v_ashrrev_i32_e32 v11, 31, v10
	v_lshlrev_b64 v[10:11], 13, v[10:11]
	v_or_b32_e32 v10, s12, v10
	v_lshl_add_u64 v[10:11], v[10:11], 0, v[18:19]
	v_lshl_add_u64 v[10:11], s[78:79], 0, v[10:11]
	v_lshl_add_u64 v[10:11], v[10:11], 0, s[10:11]
	v_mul_f32_e32 v2, v20, v2
	v_mul_f32_e32 v3, v20, v3
	v_mul_f32_e32 v4, v20, v4
	v_mul_f32_e32 v5, v20, v5
	v_cvt_pk_bf16_f32 v2, v2, v3
	v_cvt_pk_bf16_f32 v3, v4, v5
	global_store_dwordx2 v[16:17], v[2:3], off offset:1536
	s_nop 1
	v_mov_b32_e32 v2, v112
	v_mov_b32_e32 v3, v113
	v_mov_b32_e32 v4, v114
	v_mov_b32_e32 v5, v115
	v_mul_f32_e32 v2, v20, v2
	v_mul_f32_e32 v3, v20, v3
	v_mul_f32_e32 v4, v20, v4
	v_mul_f32_e32 v5, v20, v5
	v_cvt_pk_bf16_f32 v2, v2, v3
	v_cvt_pk_bf16_f32 v3, v4, v5
	global_store_dwordx2 v[16:17], v[2:3], off offset:2048
	s_nop 1
	v_mov_b32_e32 v2, v116
	v_mov_b32_e32 v3, v117
	v_mov_b32_e32 v4, v118
	v_mov_b32_e32 v5, v119
	v_mul_f32_e32 v2, v20, v2
	v_mul_f32_e32 v3, v20, v3
	v_mul_f32_e32 v4, v20, v4
	v_mul_f32_e32 v5, v20, v5
	v_cvt_pk_bf16_f32 v2, v2, v3
	v_cvt_pk_bf16_f32 v3, v4, v5
	global_store_dwordx2 v[16:17], v[2:3], off offset:2560
	s_nop 1
	v_mov_b32_e32 v2, v120
	v_mov_b32_e32 v3, v121
	v_mov_b32_e32 v4, v122
	v_mov_b32_e32 v5, v123
	v_mul_f32_e32 v2, v20, v2
	v_mul_f32_e32 v3, v20, v3
	v_mul_f32_e32 v4, v20, v4
	v_mul_f32_e32 v5, v20, v5
	v_cvt_pk_bf16_f32 v2, v2, v3
	v_cvt_pk_bf16_f32 v3, v4, v5
	global_store_dwordx2 v[16:17], v[2:3], off offset:3072
	s_nop 1
	v_mov_b32_e32 v12, v124
	v_mov_b32_e32 v13, v125
	v_mov_b32_e32 v14, v126
	v_mov_b32_e32 v15, v127
	v_and_b32_e32 v6, 15, v134
	v_mov_b32_e32 v3, 0
	v_lshl_or_b32 v2, v6, 13, s12
	v_lshl_add_u64 v[8:9], v[2:3], 0, v[18:19]
	v_lshl_add_u64 v[8:9], s[78:79], 0, v[8:9]
	v_mov_b32_e32 v4, v3
	v_mov_b32_e32 v2, v3
	v_lshl_add_u64 v[8:9], v[8:9], 0, s[8:9]
	v_mul_f32_e32 v5, v20, v12
	v_mul_f32_e32 v7, v20, v13
	v_mul_f32_e32 v13, v20, v14
	v_cvt_pk_bf16_f32 v12, v5, v7
	v_mov_b32_e32 v5, v3
	v_mul_f32_e32 v14, v20, v15
	v_cvt_pk_bf16_f32 v13, v13, v14
	global_store_dwordx2 v[16:17], v[12:13], off offset:3584
